# grid barrier: non-leader arrivers with 1,2,4,..,32 arrivals outstanding issue an early L2 write-back so the leader's release flush has less to do
# baseline (speedup 1.0000x reference)
.LBB0_227:
	s_or_b64 exec, exec, s[8:9]
	v_cvt_f32_u32_e32 v4, v2
	s_waitcnt vmcnt(0)
	v_readfirstlane_b32 s2, v3
	v_sub_u32_e32 v3, 0, v2
	v_rcp_iflag_f32_e32 v4, v4
	v_add_u32_e32 v5, s2, v1
	v_mul_f32_e32 v4, 0x4f7ffffe, v4
	v_cvt_u32_f32_e32 v4, v4
	v_mul_lo_u32 v1, v3, v4
	v_mul_hi_u32 v1, v4, v1
	v_add_u32_e32 v1, v4, v1
	v_mul_hi_u32 v1, v5, v1
	v_mul_lo_u32 v3, v1, v2
	v_sub_u32_e32 v3, v5, v3
	v_add_u32_e32 v4, 1, v1
	v_cmp_ge_u32_e32 vcc, v3, v2
	s_nop 1
	v_cndmask_b32_e32 v1, v1, v4, vcc
	v_sub_u32_e32 v4, v3, v2
	v_cndmask_b32_e32 v3, v3, v4, vcc
	v_add_u32_e32 v4, 1, v1
	v_cmp_ge_u32_e32 vcc, v3, v2
	v_add_u32_e32 v3, 1, v5
	s_nop 0
	v_cndmask_b32_e32 v1, v1, v4, vcc
	v_mul_lo_u32 v4, v2, v1
	v_add_u32_e32 v2, v4, v2
	v_cmp_ne_u32_e32 vcc, v3, v2
	s_and_saveexec_b64 s[2:3], vcc
	s_xor_b64 s[2:3], exec, s[2:3]
	s_cbranch_execz .LBB0_241
	v_sub_u32_e32 v0, v2, v3
	s_nop 0
	v_readfirstlane_b32 s8, v0
	s_add_i32 s9, s8, -1
	s_and_b32 s9, s9, s8
	s_cbranch_scc1 .Lef_0
	buffer_wbl2 sc1
.Lef_0:
	s_add_i32 s8, s24, 0x900
	s_mov_b32 s9, 0
	s_lshl_b64 s[8:9], s[8:9], 2
	v_readlane_b32 s10, v252, 0
	v_readlane_b32 s11, v252, 1
	s_add_u32 s12, s10, s8
	s_addc_u32 s13, s11, s9
	v_mov_b32_e32 v0, 0
	global_load_dword v2, v0, s[12:13] sc1
	s_waitcnt vmcnt(0)
	v_cmp_eq_u32_e32 vcc, v2, v1
	s_and_saveexec_b64 s[8:9], vcc
	s_cbranch_execz .LBB0_240
	v_readlane_b32 s16, v252, 2
	v_readlane_b32 s18, v252, 4
	v_readlane_b32 s19, v252, 5
	s_add_u32 s10, s18, 0xf210200
	v_readlane_b32 s17, v252, 3
	s_addc_u32 s11, s19, 0
	s_mov_b32 s25, 1
	s_mov_b64 s[14:15], 0
	v_readlane_b32 s20, v252, 6
	v_readlane_b32 s21, v252, 7
	v_readlane_b32 s22, v252, 8
	v_readlane_b32 s23, v252, 9
	s_branch .LBB0_231

.Lef_1:
	s_mov_b64 s[10:11], 0x3e38aa3b
	s_add_i32 s8, s22, 0x900
	s_mov_b32 s9, s11
	s_lshl_b64 s[8:9], s[8:9], 2
	v_readlane_b32 s10, v252, 0
	v_readlane_b32 s11, v252, 1
	s_add_u32 s10, s10, s8
	s_addc_u32 s11, s11, s9
	s_nop 2
	global_load_dword v0, v193, s[10:11] sc1
	s_waitcnt vmcnt(0)
	v_cmp_eq_u32_e32 vcc, v0, v1
	s_and_saveexec_b64 s[8:9], vcc
	s_cbranch_execz .LBB0_348
	s_mov_b32 s23, 1
	s_mov_b64 s[12:13], 0
	s_branch .LBB0_339
